# code placement: GEMM K-loop heads aligned to 256 bytes instead of 64 (attention loop heads stay at 64)
# baseline (speedup 1.0000x reference)
.Lgprio0:
	v_add_u32_e32 v236, 0x10000, v175
	v_add_u32_e32 v237, 0x14000, v175
	v_add_u32_e32 v238, 0x18000, v175
	v_add_u32_e32 v239, 0x1c000, v175
	.p2alignl 8, 3212836864

.Lgprio1:
	v_add_u32_e32 v236, 0x10000, v172
	v_add_u32_e32 v237, 0x14000, v172
	v_add_u32_e32 v238, 0x18000, v172
	v_add_u32_e32 v239, 0x1c000, v172
	.p2alignl 8, 3212836864

.Lgprio3:
	v_add_u32_e32 v236, 0x10000, v176
	v_add_u32_e32 v237, 0x14000, v176
	v_add_u32_e32 v238, 0x18000, v176
	v_add_u32_e32 v239, 0x1c000, v176
	.p2alignl 8, 3212836864
